# same as previous best with the unreachable cooperative-groups sync code removed
# speedup vs baseline: 1.0362x; 1.0050x over previous
; __device__ __forceinline__ unsigned xb_ld(unsigned* p)              { return __hip_atomic_load(p, __ATOMIC_RELAXED, __HIP_MEMORY_SCOPE_AGENT); }
; __device__ __forceinline__ void xcd_barrier_complete(unsigned* bar, unsigned x, unsigned& nloc, unsigned& nx) {
;     const unsigned G = gridDim.x * gridDim.y * gridDim.z;
;     unsigned sum, cnt, mine, sp = 0u;
;     for (;;) {
;         sum = 0u; cnt = 0u; mine = 0u;
; #pragma unroll
;         for (unsigned j = 0; j < 16; ++j) { const unsigned c = xb_ld(&bar[XB_XCNT(j)]); sum += c; cnt += (c > 0u) ? 1u : 0u; mine = (j == x) ? c : mine; }
;         if (sum == G) break;
;         __builtin_amdgcn_s_sleep(1);
;         if ((++sp & 255u) == 0u) { if (xb_ld(&bar[XB_TMO])) break; if (sp > XB_SPIN_CAP) { atomicAdd(&bar[XB_TMO], 1u); break; } }
;     }
;     nloc = mine > 0u ? mine : 1u; nx = cnt > 0u ? cnt : 1u;
; }
; __global__ void __launch_bounds__(NTHR, 2) trunk_fwd(Params p) {
;     ...
;     if (threadIdx.x < 16) misc[threadIdx.x] = 0u;
;     __syncthreads();
;     XcdBarrier bar = xcd_barrier_post((unsigned*)(((const Params __attribute__((address_space(4)))*)__builtin_amdgcn_kernarg_segment_ptr())->ws + WS_CTL), misc);
;     do_phase<PH_INIT>(0, 0, lds);
;     grid.sync();
.LBB0_72:
	s_or_b64 exec, exec, s[14:15]
	v_lshrrev_b32_e32 v1, 20, v0
	v_lshrrev_b32_e32 v0, 10, v0
	v_or_b32_e32 v0, v0, v1
	s_movk_i32 s0, 0x3ff
	v_and_or_b32 v0, v0, s0, v162
	v_cmp_eq_u32_e32 vcc, 0, v0
	s_barrier
	s_and_saveexec_b64 s[0:1], vcc
	s_branch .LBB0_82
.LBB0_82:
	s_or_b64 exec, exec, s[0:1]
	s_mul_i32 s1, s71, s70
	s_ashr_i32 s71, s70, 31
	s_add_u32 s78, s6, 0x1d100200
	s_addc_u32 s79, s7, 0
	s_add_u32 s82, s6, 0x1d100400
	s_addc_u32 s83, s7, 0
	s_add_u32 s84, s6, 0x1d100500
	s_addc_u32 s85, s7, 0
	s_add_u32 s86, s6, 0x1d100600
	s_addc_u32 s87, s7, 0
	s_add_u32 s90, s6, 0x1d100700
	s_addc_u32 s91, s7, 0
	s_add_u32 s92, s6, 0x1d100800
	s_addc_u32 s93, s7, 0
	s_add_u32 s96, s6, 0x1d100900
	s_addc_u32 s97, s7, 0
	s_add_u32 s44, s6, 0x1d100a00
	s_addc_u32 s45, s7, 0
	s_add_u32 s46, s6, 0x1d100b00
	s_addc_u32 s47, s7, 0
	s_add_u32 s48, s6, 0x1d100c00
	s_addc_u32 s49, s7, 0
	s_add_u32 s50, s6, 0x1d100d00
	s_addc_u32 s51, s7, 0
	s_add_u32 s52, s6, 0x1d100e00
	s_addc_u32 s53, s7, 0
	s_add_u32 s36, s6, 0x1d100f00
	s_addc_u32 s37, s7, 0
	s_add_u32 s26, s6, 0x1d101000
	s_addc_u32 s27, s7, 0
	s_add_u32 s28, s6, 0x1d101100
	s_addc_u32 s29, s7, 0
	s_barrier
	s_load_dword s0, s[68:69], 0xe0
	s_add_u32 s30, s6, 0x1d101200
	s_addc_u32 s31, s7, 0
	s_add_u32 s56, s6, 0x1d101300
	s_addc_u32 s57, s7, 0
	s_cmp_eq_u32 s33, 15
	s_waitcnt lgkmcnt(0)
	s_mul_i32 s77, s1, s0
	s_cselect_b64 s[0:1], -1, 0
	s_cmp_eq_u32 s33, 14
	v_writelane_b32 v240, s0, 0
	v_mov_b32_e32 v164, 0x358637bd
	s_mov_b32 s35, 0x800000
	v_writelane_b32 v240, s1, 1
	s_cselect_b64 s[0:1], -1, 0
	v_writelane_b32 v240, s0, 2
	s_cmp_eq_u32 s33, 13
	v_mov_b32_e32 v1, 0
	v_writelane_b32 v240, s1, 3
	s_cselect_b64 s[0:1], -1, 0
	v_writelane_b32 v240, s0, 4
	s_cmp_eq_u32 s33, 12
	v_mov_b32_e32 v165, 1
	v_writelane_b32 v240, s1, 5
	s_cselect_b64 s[0:1], -1, 0
	v_writelane_b32 v240, s0, 6
	s_cmp_eq_u32 s33, 11
	v_mov_b32_e32 v166, 0x3ecc95a3
	v_writelane_b32 v240, s1, 7
	s_cselect_b64 s[0:1], -1, 0
	v_writelane_b32 v240, s0, 8
	s_cmp_eq_u32 s33, 10
	v_mov_b32_e32 v167, 0x3a27c5ac
	v_writelane_b32 v240, s1, 9
	s_cselect_b64 s[0:1], -1, 0
	v_writelane_b32 v240, s0, 10
	s_cmp_eq_u32 s33, 9
	v_mov_b32_e32 v168, 0xff800000
	v_writelane_b32 v240, s1, 11
	s_cselect_b64 s[0:1], -1, 0
	v_writelane_b32 v240, s0, 12
	s_cmp_eq_u32 s33, 8
	v_mov_b32_e32 v169, 0x42800000
	v_writelane_b32 v240, s1, 13
	s_cselect_b64 s[0:1], -1, 0
	v_writelane_b32 v240, s0, 14
	s_cmp_eq_u32 s33, 7
	v_mov_b32_e32 v146, 0x3f317218
	v_writelane_b32 v240, s1, 15
	s_cselect_b64 s[0:1], -1, 0
	v_writelane_b32 v240, s0, 16
	s_cmp_eq_u32 s33, 6
	v_mov_b32_e32 v170, 0x7fc00000
	v_writelane_b32 v240, s1, 17
	s_cselect_b64 s[0:1], -1, 0
	v_writelane_b32 v240, s0, 18
	s_cmp_eq_u32 s33, 5
	v_mov_b32_e32 v171, 0x3c00
	v_writelane_b32 v240, s1, 19
	s_cselect_b64 s[0:1], -1, 0
	v_writelane_b32 v240, s0, 20
	s_cmp_eq_u32 s33, 4
	v_not_b32_e32 v172, 63
	v_writelane_b32 v240, s1, 21
	s_cselect_b64 s[0:1], -1, 0
	v_writelane_b32 v240, s0, 22
	s_cmp_eq_u32 s33, 3
	v_mov_b32_e32 v173, 0x7f800000
	v_writelane_b32 v240, s1, 23
	s_cselect_b64 s[0:1], -1, 0
	v_writelane_b32 v240, s0, 24
	s_cmp_eq_u32 s33, 2
	s_mov_b32 s42, 0x10000
	v_writelane_b32 v240, s1, 25
	s_cselect_b64 s[0:1], -1, 0
	v_writelane_b32 v240, s0, 26
	s_cmp_eq_u32 s33, 1
	s_mov_b32 s43, 0x14000
	v_writelane_b32 v240, s1, 27
	s_cselect_b64 s[0:1], -1, 0
	v_writelane_b32 v240, s0, 28
	s_cmp_eq_u32 s33, 0
	s_mov_b32 s66, 0x1c000
	v_writelane_b32 v240, s1, 29
	s_cselect_b64 s[0:1], -1, 0
	v_writelane_b32 v240, s0, 30
	s_mov_b32 s63, 0xc000
	s_movk_i32 s64, 0x90
	v_writelane_b32 v240, s1, 31
	s_lshl_b32 s0, s33, 8
	s_add_u32 s0, s8, s0
	s_addc_u32 s1, s9, 0
	s_add_u32 s2, s0, 0x1400
	s_addc_u32 s3, s1, 0
	v_writelane_b32 v240, s2, 32
	s_add_u32 s0, s0, 0x2400
	s_addc_u32 s1, s1, 0
	v_writelane_b32 v240, s3, 33
	v_writelane_b32 v240, s0, 34
	s_movk_i32 s88, 0x110
	s_movk_i32 s65, 0x1e00
	v_writelane_b32 v240, s1, 35
	s_add_u32 s0, s6, 0x1d103400
	s_addc_u32 s1, s7, 0
	v_writelane_b32 v240, s0, 36
	s_mov_b64 s[14:15], 0
	s_mov_b64 s[80:81], 0x80
	v_writelane_b32 v240, s1, 37
	s_add_u32 s0, s6, 0x1d103500
	s_addc_u32 s1, s7, 0
	v_writelane_b32 v240, s0, 38
	s_ashr_i32 s75, s74, 31
	s_add_i32 s33, 0, 0x1c800
	v_writelane_b32 v240, s1, 39
	s_lshl_b32 s0, s70, 7
	v_writelane_b32 v240, s0, 40
	s_lshl_b32 s0, s70, 2
	v_writelane_b32 v240, s0, 41
	s_add_i32 s0, 0, 0x20100
	v_writelane_b32 v240, s0, 42
	s_add_i32 s0, 0, 0x20040
	v_writelane_b32 v240, s0, 43
	s_add_i32 s0, 0, 0x20044
	v_writelane_b32 v240, s0, 44
	s_add_i32 s0, 0, 0x16800
	v_writelane_b32 v240, s0, 45
	s_add_i32 s0, 0, 0x16200
	v_writelane_b32 v240, s0, 46
	s_add_i32 s0, 0, 0x17400
	v_writelane_b32 v240, s0, 47
	s_add_i32 s0, 0, 0x5100
	v_writelane_b32 v240, s0, 48
	s_add_i32 s0, 0, 0x1a800
	v_writelane_b32 v240, s0, 49
	s_add_i32 s0, 0, 0x13c00
	v_writelane_b32 v240, s0, 50
	s_lshl_b64 s[0:1], s[74:75], 12
	v_writelane_b32 v240, s0, 51
	s_mov_b32 s89, 0
	s_nop 0
	v_writelane_b32 v240, s1, 52
	s_lshl_b64 s[0:1], s[74:75], 11
	v_writelane_b32 v240, s0, 53
	s_nop 1
	v_writelane_b32 v240, s1, 54
	v_writelane_b32 v240, s67, 55
	v_writelane_b32 v240, s68, 56
	s_mov_b32 s0, s70
	s_nop 0
	v_writelane_b32 v240, s69, 57
	v_writelane_b32 v240, s0, 58
	s_nop 1
	v_writelane_b32 v240, s1, 59
	v_writelane_b32 v240, s72, 60
	s_mov_b32 s0, s74
	s_nop 0
	v_writelane_b32 v240, s73, 61
	v_writelane_b32 v240, s0, 62
	s_nop 1
	v_writelane_b32 v240, s1, 63
	s_mov_b32 s0, s76
	v_writelane_b32 v239, s0, 0
	s_nop 1
	v_writelane_b32 v239, s1, 1
	v_writelane_b32 v239, s71, 2
	v_writelane_b32 v239, s77, 3
	v_writelane_b32 v239, s78, 4
	s_nop 1
	v_writelane_b32 v239, s79, 5
	v_writelane_b32 v239, s82, 6
	s_nop 1
	v_writelane_b32 v239, s83, 7
	v_writelane_b32 v239, s84, 8
	s_nop 1
	v_writelane_b32 v239, s85, 9
	v_writelane_b32 v239, s86, 10
	s_nop 1
	v_writelane_b32 v239, s87, 11
	v_writelane_b32 v239, s90, 12
	s_nop 1
	v_writelane_b32 v239, s91, 13
	v_writelane_b32 v239, s92, 14
	s_nop 1
	v_writelane_b32 v239, s93, 15
	v_writelane_b32 v239, s96, 16
	s_nop 1
	v_writelane_b32 v239, s97, 17
	v_writelane_b32 v239, s44, 18
	s_nop 1
	v_writelane_b32 v239, s45, 19
	v_writelane_b32 v239, s46, 20
	s_nop 1
	v_writelane_b32 v239, s47, 21
	v_writelane_b32 v239, s48, 22
	s_nop 1
	v_writelane_b32 v239, s49, 23
	v_writelane_b32 v239, s50, 24
	s_nop 1
	v_writelane_b32 v239, s51, 25
	v_writelane_b32 v239, s52, 26
	s_nop 1
	v_writelane_b32 v239, s53, 27
	v_writelane_b32 v239, s36, 28
	s_nop 1
	v_writelane_b32 v239, s37, 29
	v_writelane_b32 v239, s26, 30
	s_nop 1
	v_writelane_b32 v239, s27, 31
	v_writelane_b32 v239, s28, 32
	s_nop 1
	v_writelane_b32 v239, s29, 33
	v_writelane_b32 v239, s30, 34
	s_nop 1
	v_writelane_b32 v239, s31, 35
	v_writelane_b32 v239, s56, 36
	s_nop 1
	v_writelane_b32 v239, s57, 37
	s_mov_b32 s99, 1
	s_branch .LBB0_114
